# latent attention: two key tiles per super-step handled by one hand-scheduled body (QK of tile j+1 and PV of tile j issued inside the softmax VALU streams, permlane32_swap row max)
# baseline (speedup 1.0000x reference)
.LBB0_557:
	s_and_b64 vcc, exec, s[14:15]
	s_cbranch_vccnz .Lap_pair
	v_add_u32_e32 v109, s16, v240
	v_add_u32_e32 v108, v109, v241
	ds_read_b128 v[34:37], v108
	ds_read_b128 v[102:105], v108 offset:32
	s_cmp_ge_i32 s52, s36
	s_waitcnt lgkmcnt(1)
	v_mfma_f32_32x32x16_bf16 v[50:65], v[34:37], v[66:69], 0
	ds_read_b128 v[34:37], v108 offset:4608
	s_waitcnt lgkmcnt(1)
	v_mfma_f32_32x32x16_bf16 v[50:65], v[102:105], v[70:73], v[50:65]
	ds_read_b128 v[102:105], v108 offset:4640
	s_waitcnt lgkmcnt(1)
	v_mfma_f32_32x32x16_bf16 v[34:49], v[34:37], v[66:69], 0
	s_waitcnt lgkmcnt(0)
	v_mfma_f32_32x32x16_bf16 v[34:49], v[102:105], v[70:73], v[34:49]
	ds_read_b128 v[102:105], v108 offset:64
	s_waitcnt lgkmcnt(0)
	v_mfma_f32_32x32x16_bf16 v[50:65], v[102:105], v[74:77], v[50:65]
	ds_read_b128 v[102:105], v108 offset:4672
	s_waitcnt lgkmcnt(0)
	v_mfma_f32_32x32x16_bf16 v[34:49], v[102:105], v[74:77], v[34:49]
	ds_read_b128 v[102:105], v108 offset:96
	s_waitcnt lgkmcnt(0)
	v_mfma_f32_32x32x16_bf16 v[50:65], v[102:105], v[78:81], v[50:65]
	ds_read_b128 v[102:105], v108 offset:4704
	s_waitcnt lgkmcnt(0)
	v_mfma_f32_32x32x16_bf16 v[34:49], v[102:105], v[78:81], v[34:49]
	s_cbranch_scc1 .LBB0_564
	s_add_i32 s54, s44, s52
	s_cmp_lt_i32 s54, 2
	s_cbranch_scc1 .LBB0_560
	s_cmp_eq_u32 s54, 2
	s_cselect_b64 s[16:17], -1, 0
	s_cbranch_execz .LBB0_561
	s_branch .LBB0_562

.LBB0_564:
	s_nop 7
	v_max_f32_e32 v102, v51, v51
	v_max_f32_e32 v103, v50, v50
	v_max_f32_e32 v102, v103, v102
	v_max3_f32 v102, v102, v52, v53
	v_max3_f32 v102, v102, v54, v55
	v_max3_f32 v102, v102, v56, v57
	v_max3_f32 v102, v102, v58, v59
	v_max3_f32 v102, v102, v60, v61
	v_max3_f32 v102, v102, v62, v63
	v_max3_f32 v102, v102, v64, v65
	v_max3_f32 v102, v102, v34, v35
	v_max3_f32 v102, v102, v36, v37
	v_max3_f32 v102, v102, v38, v39
	v_max3_f32 v102, v102, v40, v41
	v_and_b32_e32 v103, 64, v226
	v_max3_f32 v102, v102, v42, v43
	v_xor_b32_e32 v104, 32, v226
	v_add_u32_e32 v105, 64, v103
	v_max3_f32 v102, v102, v44, v45
	v_cmp_lt_i32_e32 vcc, v104, v105
	v_max3_f32 v102, v102, v46, v47
	v_max3_f32 v102, v102, v48, v49
	v_cndmask_b32_e32 v103, v226, v104, vcc
	v_lshlrev_b32_e32 v110, 2, v103
	ds_bpermute_b32 v103, v110, v102
	v_add_u32_e32 v109, v109, v150
	s_andn2_b64 vcc, exec, s[14:15]
	s_waitcnt lgkmcnt(0)
	v_max3_f32 v107, v0, v102, v103
	v_sub_f32_e32 v118, v0, v107
	v_sub_f32_e32 v0, v50, v107
	v_exp_f32_e32 v119, v0
	v_sub_f32_e32 v0, v34, v107
	v_exp_f32_e32 v120, v0
	v_sub_f32_e32 v0, v51, v107
	v_sub_f32_e32 v34, v35, v107
	v_exp_f32_e32 v0, v0
	v_exp_f32_e32 v102, v34
	v_add_f32_e32 v103, v120, v119
	v_pk_add_f32 v[34:35], v[102:103], v[0:1]
	s_nop 0
	v_pk_add_f32 v[50:51], v[34:35], v[34:35] op_sel_hi:[0,1]
	v_sub_f32_e32 v34, v52, v107
	v_exp_f32_e32 v103, v34
	v_sub_f32_e32 v34, v36, v107
	v_exp_f32_e32 v121, v34
	v_sub_f32_e32 v34, v53, v107
	v_exp_f32_e32 v50, v34
	v_sub_f32_e32 v34, v37, v107
	v_exp_f32_e32 v34, v34
	v_add_f32_e32 v35, v121, v103
	v_pk_add_f32 v[36:37], v[34:35], v[50:51]
	v_sub_f32_e32 v35, v54, v107
	v_pk_add_f32 v[52:53], v[36:37], v[36:37] op_sel_hi:[0,1]
	v_exp_f32_e32 v51, v35
	v_sub_f32_e32 v35, v38, v107
	v_sub_f32_e32 v36, v55, v107
	v_exp_f32_e32 v35, v35
	v_exp_f32_e32 v52, v36
	v_sub_f32_e32 v36, v39, v107
	v_exp_f32_e32 v36, v36
	v_add_f32_e32 v37, v35, v51
	v_pk_add_f32 v[38:39], v[36:37], v[52:53]
	v_sub_f32_e32 v37, v56, v107
	v_pk_add_f32 v[54:55], v[38:39], v[38:39] op_sel_hi:[0,1]
	v_exp_f32_e32 v53, v37
	v_sub_f32_e32 v37, v40, v107
	v_sub_f32_e32 v38, v57, v107
	v_exp_f32_e32 v37, v37
	v_exp_f32_e32 v54, v38
	v_sub_f32_e32 v38, v41, v107
	v_exp_f32_e32 v112, v38
	v_add_f32_e32 v113, v37, v53
	v_cvt_pk_bf16_f32 v40, v35, v36
	v_pk_add_f32 v[38:39], v[112:113], v[54:55]
	s_nop 0
	v_pk_add_f32 v[56:57], v[38:39], v[38:39] op_sel_hi:[0,1]
	v_sub_f32_e32 v38, v58, v107
	v_exp_f32_e32 v55, v38
	v_sub_f32_e32 v38, v42, v107
	v_exp_f32_e32 v113, v38
	v_sub_f32_e32 v38, v59, v107
	v_exp_f32_e32 v56, v38
	v_sub_f32_e32 v38, v43, v107
	v_exp_f32_e32 v114, v38
	v_add_f32_e32 v115, v113, v55
	v_cvt_pk_bf16_f32 v41, v37, v112
	v_cvt_pk_bf16_f32 v42, v55, v56
	v_pk_add_f32 v[38:39], v[114:115], v[56:57]
	s_nop 0
	v_pk_add_f32 v[58:59], v[38:39], v[38:39] op_sel_hi:[0,1]
	v_sub_f32_e32 v38, v60, v107
	v_exp_f32_e32 v43, v38
	v_sub_f32_e32 v38, v44, v107
	v_exp_f32_e32 v57, v38
	v_sub_f32_e32 v38, v61, v107
	v_exp_f32_e32 v58, v38
	v_sub_f32_e32 v38, v45, v107
	v_exp_f32_e32 v116, v38
	v_add_f32_e32 v117, v57, v43
	v_cvt_pk_bf16_f32 v43, v43, v58
	v_pk_add_f32 v[38:39], v[116:117], v[58:59]
	s_nop 0
	v_pk_add_f32 v[44:45], v[38:39], v[38:39] op_sel_hi:[0,1]
	v_sub_f32_e32 v38, v62, v107
	v_exp_f32_e32 v59, v38
	v_sub_f32_e32 v38, v46, v107
	v_exp_f32_e32 v115, v38
	v_sub_f32_e32 v38, v63, v107
	v_exp_f32_e32 v44, v38
	v_sub_f32_e32 v38, v47, v107
	v_exp_f32_e32 v60, v38
	v_add_f32_e32 v61, v115, v59
	v_cvt_pk_bf16_f32 v35, v57, v116
	v_add_u32_e32 v58, 0x3000, v109
	v_pk_add_f32 v[38:39], v[60:61], v[44:45]
	v_cvt_pk_bf16_f32 v44, v59, v44
	v_pk_add_f32 v[46:47], v[38:39], v[38:39] op_sel_hi:[0,1]
	v_sub_f32_e32 v38, v64, v107
	v_exp_f32_e32 v45, v38
	v_sub_f32_e32 v38, v48, v107
	v_exp_f32_e32 v48, v38
	v_sub_f32_e32 v38, v65, v107
	v_exp_f32_e32 v46, v38
	v_sub_f32_e32 v38, v49, v107
	v_exp_f32_e32 v62, v38
	v_add_f32_e32 v63, v48, v45
	v_cvt_pk_bf16_f32 v45, v45, v46
	v_cvt_pk_bf16_f32 v49, v53, v54
	v_pk_add_f32 v[38:39], v[62:63], v[46:47]
	v_cvt_pk_bf16_f32 v46, v119, v0
	v_add_f32_e32 v106, v38, v39
	v_exp_f32_e32 v38, v118
	v_add_u32_e32 v0, 0x2000, v109
	v_cvt_pk_bf16_f32 v37, v48, v62
	v_cvt_pk_bf16_f32 v47, v103, v50
	v_cvt_pk_bf16_f32 v48, v51, v52
	ds_read2_b64 v[50:53], v0 offset0:128 offset1:130
	ds_read2_b64 v[54:57], v0 offset0:132 offset1:134
	v_pk_mul_f32 v[32:33], v[32:33], v[38:39] op_sel_hi:[1,0]
	v_pk_mul_f32 v[30:31], v[30:31], v[38:39] op_sel_hi:[1,0]
	v_pk_mul_f32 v[28:29], v[28:29], v[38:39] op_sel_hi:[1,0]
	v_pk_mul_f32 v[26:27], v[26:27], v[38:39] op_sel_hi:[1,0]
	v_pk_mul_f32 v[24:25], v[24:25], v[38:39] op_sel_hi:[1,0]
	v_pk_mul_f32 v[22:23], v[22:23], v[38:39] op_sel_hi:[1,0]
	v_pk_mul_f32 v[20:21], v[20:21], v[38:39] op_sel_hi:[1,0]
	v_pk_mul_f32 v[18:19], v[18:19], v[38:39] op_sel_hi:[1,0]
	v_pk_mul_f32 v[16:17], v[16:17], v[38:39] op_sel_hi:[1,0]
	v_pk_mul_f32 v[14:15], v[14:15], v[38:39] op_sel_hi:[1,0]
	s_waitcnt lgkmcnt(1)
	v_mfma_f32_32x32x16_bf16 v[18:33], v[50:53], v[46:49], v[18:33]
	ds_read2_b64 v[50:53], v58 offset0:192 offset1:194
	v_mul_f32_e64 v12, v12, v38
	v_mul_f32_e64 v13, v13, v38
	v_mul_f32_e64 v10, v10, v38
	v_mul_f32_e64 v11, v11, v38
	v_pk_mul_f32 v[8:9], v[8:9], v[38:39] op_sel_hi:[1,0]
	v_pk_mul_f32 v[6:7], v[6:7], v[38:39] op_sel_hi:[1,0]
	v_pk_mul_f32 v[4:5], v[4:5], v[38:39] op_sel_hi:[1,0]
	v_pk_mul_f32 v[2:3], v[2:3], v[38:39] op_sel_hi:[1,0]
	s_waitcnt lgkmcnt(1)
	v_mfma_f32_32x32x16_bf16 v[18:33], v[54:57], v[42:45], v[18:33]
	v_fmac_f32_e32 v106, v111, v38
	v_cvt_pk_bf16_f32 v38, v120, v102
	v_cvt_pk_bf16_f32 v39, v121, v34
	v_cvt_pk_bf16_f32 v34, v113, v114
	v_cvt_pk_bf16_f32 v36, v115, v60
	s_waitcnt lgkmcnt(0)
	v_mfma_f32_32x32x16_bf16 v[2:17], v[50:53], v[46:49], v[2:17]
	ds_read2_b64 v[46:49], v58 offset0:196 offset1:198
	s_waitcnt lgkmcnt(0)
	v_mfma_f32_32x32x16_bf16 v[2:17], v[46:49], v[42:45], v[2:17]
	ds_read2_b64 v[42:45], v0 offset0:136 offset1:138
	s_waitcnt lgkmcnt(0)
	v_mfma_f32_32x32x16_bf16 v[18:33], v[42:45], v[38:41], v[18:33]
	ds_read2_b64 v[42:45], v58 offset0:200 offset1:202
	s_waitcnt lgkmcnt(0)
	v_mfma_f32_32x32x16_bf16 v[2:17], v[42:45], v[38:41], v[2:17]
	ds_read2_b64 v[38:41], v0 offset0:140 offset1:142
	s_waitcnt lgkmcnt(0)
	v_mfma_f32_32x32x16_bf16 v[18:33], v[38:41], v[34:37], v[18:33]
	ds_read2_b64 v[38:41], v58 offset0:204 offset1:206
	s_waitcnt lgkmcnt(0)
	v_mfma_f32_32x32x16_bf16 v[2:17], v[38:41], v[34:37], v[2:17]
.LBB0_573:
	s_xor_b32 s45, s45, 2
	s_andn2_b64 vcc, exec, s[12:13]
	v_add_u32_e32 v99, 0x80, v99
	s_cbranch_vccz .LBB0_385
	v_mov_b32_e32 v111, v106
	s_mov_b32 s52, s51
	v_mov_b32_e32 v0, v107
	s_branch .LBB0_551

.Lap_pair:
	v_add_u32_e32 v109, s16, v240
	v_add_u32_e32 v108, v109, v241
	ds_read_b128 v[192:195], v108
	ds_read_b128 v[196:199], v108 offset:4608
	ds_read_b128 v[200:203], v108 offset:32
	ds_read_b128 v[204:207], v108 offset:4640
	ds_read_b128 v[208:211], v108 offset:64
	ds_read_b128 v[212:215], v108 offset:4672
	ds_read_b128 v[216:219], v108 offset:96
	ds_read_b128 v[220:223], v108 offset:4704
	v_add_u32_e32 v247, v109, v150
	v_add_u32_e32 v243, 0x2000, v247
	v_add_u32_e32 v244, 0x3000, v247
	v_add_u32_e32 v246, 0x7800, v247
	v_add_u32_e32 v247, 0x6800, v247
	v_xor_b32_e32 v104, 32, v226
	v_and_b32_e32 v105, 64, v226
	v_add_u32_e32 v105, 64, v105
	s_waitcnt lgkmcnt(7)
	v_mfma_f32_32x32x16_bf16 v[50:65], v[192:195], v[66:69], 0
	s_waitcnt lgkmcnt(6)
	v_mfma_f32_32x32x16_bf16 v[34:49], v[196:199], v[66:69], 0
	s_waitcnt lgkmcnt(5)
	v_mfma_f32_32x32x16_bf16 v[50:65], v[200:203], v[70:73], v[50:65]
	s_waitcnt lgkmcnt(4)
	v_mfma_f32_32x32x16_bf16 v[34:49], v[204:207], v[70:73], v[34:49]
	s_waitcnt lgkmcnt(3)
	v_mfma_f32_32x32x16_bf16 v[50:65], v[208:211], v[74:77], v[50:65]
	s_waitcnt lgkmcnt(2)
	v_mfma_f32_32x32x16_bf16 v[34:49], v[212:215], v[74:77], v[34:49]
	s_waitcnt lgkmcnt(1)
	v_mfma_f32_32x32x16_bf16 v[50:65], v[216:219], v[78:81], v[50:65]
	s_waitcnt lgkmcnt(0)
	v_mfma_f32_32x32x16_bf16 v[34:49], v[220:223], v[78:81], v[34:49]
	ds_read_b128 v[192:195], v108 offset:18432
	ds_read_b128 v[196:199], v108 offset:23040
	ds_read_b128 v[200:203], v108 offset:18464
	ds_read_b128 v[204:207], v108 offset:23072
	ds_read_b128 v[208:211], v108 offset:18496
	ds_read_b128 v[212:215], v108 offset:23104
	ds_read_b128 v[216:219], v108 offset:18528
	ds_read_b128 v[220:223], v108 offset:23136
	ds_read2_b64 v[122:125], v243 offset0:128 offset1:130
	ds_read2_b64 v[126:129], v244 offset0:192 offset1:194
	ds_read2_b64 v[130:133], v243 offset0:132 offset1:134
	ds_read2_b64 v[134:137], v244 offset0:196 offset1:198
	s_cmp_ge_i32 s52, s36
	s_cbranch_scc1 .Lap_nomask0
	s_add_i32 s54, s44, s52
	s_abs_i32 s54, s54
	s_cmp_lg_u32 s54, 2
	s_cbranch_scc1 .Lap_nomask0
	v_mov_b32_e32 v120, v99
	v_cmp_lt_u32_e32 vcc, s33, v120
	v_add_u32_e32 v245, 32, v99
	s_nop 0
	v_cndmask_b32_e32 v50, v234, v50, vcc
	v_cmp_lt_u32_e32 vcc, s33, v245
	v_add_u32_e32 v120, 1, v99
	s_nop 0
	v_cndmask_b32_e32 v34, v234, v34, vcc
	v_cmp_lt_u32_e32 vcc, s33, v120
	v_add_u32_e32 v245, 33, v99
	s_nop 0
	v_cndmask_b32_e32 v51, v234, v51, vcc
	v_cmp_lt_u32_e32 vcc, s33, v245
	v_add_u32_e32 v120, 2, v99
	s_nop 0
	v_cndmask_b32_e32 v35, v234, v35, vcc
	v_cmp_lt_u32_e32 vcc, s33, v120
	v_add_u32_e32 v245, 34, v99
	s_nop 0
	v_cndmask_b32_e32 v52, v234, v52, vcc
	v_cmp_lt_u32_e32 vcc, s33, v245
	v_add_u32_e32 v120, 3, v99
	s_nop 0
	v_cndmask_b32_e32 v36, v234, v36, vcc
	v_cmp_lt_u32_e32 vcc, s33, v120
	v_add_u32_e32 v245, 35, v99
	s_nop 0
	v_cndmask_b32_e32 v53, v234, v53, vcc
	v_cmp_lt_u32_e32 vcc, s33, v245
	v_add_u32_e32 v120, 8, v99
	s_nop 0
	v_cndmask_b32_e32 v37, v234, v37, vcc
	v_cmp_lt_u32_e32 vcc, s33, v120
	v_add_u32_e32 v245, 40, v99
	s_nop 0
	v_cndmask_b32_e32 v54, v234, v54, vcc
	v_cmp_lt_u32_e32 vcc, s33, v245
	v_add_u32_e32 v120, 9, v99
	s_nop 0
	v_cndmask_b32_e32 v38, v234, v38, vcc
	v_cmp_lt_u32_e32 vcc, s33, v120
	v_add_u32_e32 v245, 41, v99
	s_nop 0
	v_cndmask_b32_e32 v55, v234, v55, vcc
	v_cmp_lt_u32_e32 vcc, s33, v245
	v_add_u32_e32 v120, 10, v99
	s_nop 0
	v_cndmask_b32_e32 v39, v234, v39, vcc
	v_cmp_lt_u32_e32 vcc, s33, v120
	v_add_u32_e32 v245, 42, v99
	s_nop 0
	v_cndmask_b32_e32 v56, v234, v56, vcc
	v_cmp_lt_u32_e32 vcc, s33, v245
	v_add_u32_e32 v120, 11, v99
	s_nop 0
	v_cndmask_b32_e32 v40, v234, v40, vcc
	v_cmp_lt_u32_e32 vcc, s33, v120
	v_add_u32_e32 v245, 43, v99
	s_nop 0
	v_cndmask_b32_e32 v57, v234, v57, vcc
	v_cmp_lt_u32_e32 vcc, s33, v245
	v_add_u32_e32 v120, 16, v99
	s_nop 0
	v_cndmask_b32_e32 v41, v234, v41, vcc
	v_cmp_lt_u32_e32 vcc, s33, v120
	v_add_u32_e32 v245, 48, v99
	s_nop 0
	v_cndmask_b32_e32 v58, v234, v58, vcc
	v_cmp_lt_u32_e32 vcc, s33, v245
	v_add_u32_e32 v120, 17, v99
	s_nop 0
	v_cndmask_b32_e32 v42, v234, v42, vcc
	v_cmp_lt_u32_e32 vcc, s33, v120
	v_add_u32_e32 v245, 49, v99
	s_nop 0
	v_cndmask_b32_e32 v59, v234, v59, vcc
	v_cmp_lt_u32_e32 vcc, s33, v245
	v_add_u32_e32 v120, 18, v99
	s_nop 0
	v_cndmask_b32_e32 v43, v234, v43, vcc
	v_cmp_lt_u32_e32 vcc, s33, v120
	v_add_u32_e32 v245, 50, v99
	s_nop 0
	v_cndmask_b32_e32 v60, v234, v60, vcc
	v_cmp_lt_u32_e32 vcc, s33, v245
	v_add_u32_e32 v120, 19, v99
	s_nop 0
	v_cndmask_b32_e32 v44, v234, v44, vcc
	v_cmp_lt_u32_e32 vcc, s33, v120
	v_add_u32_e32 v245, 51, v99
	s_nop 0
	v_cndmask_b32_e32 v61, v234, v61, vcc
	v_cmp_lt_u32_e32 vcc, s33, v245
	v_add_u32_e32 v120, 24, v99
	s_nop 0
	v_cndmask_b32_e32 v45, v234, v45, vcc
	v_cmp_lt_u32_e32 vcc, s33, v120
	v_add_u32_e32 v245, 56, v99
	s_nop 0
	v_cndmask_b32_e32 v62, v234, v62, vcc
	v_cmp_lt_u32_e32 vcc, s33, v245
	v_add_u32_e32 v120, 25, v99
	s_nop 0
	v_cndmask_b32_e32 v46, v234, v46, vcc
	v_cmp_lt_u32_e32 vcc, s33, v120
	v_add_u32_e32 v245, 57, v99
	s_nop 0
	v_cndmask_b32_e32 v63, v234, v63, vcc
	v_cmp_lt_u32_e32 vcc, s33, v245
	v_add_u32_e32 v120, 26, v99
	s_nop 0
	v_cndmask_b32_e32 v47, v234, v47, vcc
	v_cmp_lt_u32_e32 vcc, s33, v120
	v_add_u32_e32 v245, 58, v99
	s_nop 0
	v_cndmask_b32_e32 v64, v234, v64, vcc
	v_cmp_lt_u32_e32 vcc, s33, v245
	v_add_u32_e32 v120, 27, v99
	s_nop 0
	v_cndmask_b32_e32 v48, v234, v48, vcc
	v_cmp_lt_u32_e32 vcc, s33, v120
	v_add_u32_e32 v245, 59, v99
	s_nop 0
	v_cndmask_b32_e32 v65, v234, v65, vcc
	v_cmp_lt_u32_e32 vcc, s33, v245
	s_nop 0
	s_nop 0
	v_cndmask_b32_e32 v49, v234, v49, vcc
.Lap_nomask0:
	v_max3_f32 v102, v50, v51, v52
	v_max3_f32 v103, v34, v35, v36
	v_max3_f32 v102, v102, v53, v54
	v_max3_f32 v103, v103, v37, v38
	v_max3_f32 v102, v102, v55, v56
	v_max3_f32 v103, v103, v39, v40
	v_max3_f32 v102, v102, v57, v58
	v_max3_f32 v103, v103, v41, v42
	v_max3_f32 v102, v102, v59, v60
	v_max3_f32 v103, v103, v43, v44
	v_max3_f32 v102, v102, v61, v62
	v_max3_f32 v103, v103, v45, v46
	v_max3_f32 v102, v102, v63, v64
	v_max3_f32 v103, v103, v47, v48
	s_waitcnt lgkmcnt(11)
	v_mfma_f32_32x32x16_bf16 v[160:175], v[192:195], v[66:69], 0
	v_max3_f32 v102, v102, v65, v49
	v_max_f32_e32 v102, v102, v103
	v_mov_b32_e32 v110, v102
	s_nop 1
	v_permlane32_swap_b32_e32 v110, v102
	s_nop 1
	v_max3_f32 v112, v0, v110, v102
	v_sub_f32_e32 v120, v0, v112
	v_sub_f32_e32 v50, v50, v112
	v_sub_f32_e32 v51, v51, v112
	v_exp_f32_e32 v114, v120
	v_exp_f32_e32 v50, v50
	v_sub_f32_e32 v52, v52, v112
	v_exp_f32_e32 v51, v51
	v_sub_f32_e32 v53, v53, v112
	v_exp_f32_e32 v52, v52
	s_waitcnt lgkmcnt(10)
	v_mfma_f32_32x32x16_bf16 v[176:191], v[196:199], v[66:69], 0
	v_sub_f32_e32 v54, v54, v112
	v_exp_f32_e32 v53, v53
	v_sub_f32_e32 v55, v55, v112
	v_exp_f32_e32 v54, v54
	v_sub_f32_e32 v56, v56, v112
	v_exp_f32_e32 v55, v55
	v_sub_f32_e32 v57, v57, v112
	v_exp_f32_e32 v56, v56
	v_sub_f32_e32 v58, v58, v112
	v_exp_f32_e32 v57, v57
	v_sub_f32_e32 v59, v59, v112
	v_exp_f32_e32 v58, v58
	v_sub_f32_e32 v60, v60, v112
	v_exp_f32_e32 v59, v59
	v_sub_f32_e32 v61, v61, v112
	v_exp_f32_e32 v60, v60
	s_waitcnt lgkmcnt(9)
	v_mfma_f32_32x32x16_bf16 v[160:175], v[200:203], v[70:73], v[160:175]
	v_sub_f32_e32 v62, v62, v112
	v_exp_f32_e32 v61, v61
	v_sub_f32_e32 v63, v63, v112
	v_exp_f32_e32 v62, v62
	v_sub_f32_e32 v64, v64, v112
	v_exp_f32_e32 v63, v63
	v_sub_f32_e32 v65, v65, v112
	v_exp_f32_e32 v64, v64
	v_exp_f32_e32 v65, v65
	v_sub_f32_e32 v34, v34, v112
	v_sub_f32_e32 v35, v35, v112
	v_exp_f32_e32 v34, v34
	v_pk_add_f32 v[116:117], v[50:51], v[52:53]
	v_sub_f32_e32 v36, v36, v112
	s_waitcnt lgkmcnt(8)
	v_mfma_f32_32x32x16_bf16 v[176:191], v[204:207], v[70:73], v[176:191]
	v_exp_f32_e32 v35, v35
	v_sub_f32_e32 v37, v37, v112
	v_pk_add_f32 v[118:119], v[54:55], v[56:57]
	v_exp_f32_e32 v36, v36
	v_sub_f32_e32 v38, v38, v112
	v_exp_f32_e32 v37, v37
	v_pk_add_f32 v[116:117], v[116:117], v[58:59]
	v_sub_f32_e32 v39, v39, v112
	v_exp_f32_e32 v38, v38
	v_sub_f32_e32 v40, v40, v112
	v_pk_add_f32 v[118:119], v[118:119], v[60:61]
	v_exp_f32_e32 v39, v39
	v_sub_f32_e32 v41, v41, v112
	v_exp_f32_e32 v40, v40
	s_waitcnt lgkmcnt(7)
	v_mfma_f32_32x32x16_bf16 v[160:175], v[208:211], v[74:77], v[160:175]
	v_pk_add_f32 v[116:117], v[116:117], v[62:63]
	v_sub_f32_e32 v42, v42, v112
	v_exp_f32_e32 v41, v41
	v_sub_f32_e32 v43, v43, v112
	v_pk_add_f32 v[118:119], v[118:119], v[64:65]
	v_exp_f32_e32 v42, v42
	v_sub_f32_e32 v44, v44, v112
	v_exp_f32_e32 v43, v43
	v_cvt_pk_bf16_f32 v50, v50, v51
	v_sub_f32_e32 v45, v45, v112
	v_exp_f32_e32 v44, v44
	v_sub_f32_e32 v46, v46, v112
	v_cvt_pk_bf16_f32 v51, v52, v53
	v_exp_f32_e32 v45, v45
	s_waitcnt lgkmcnt(6)
	v_mfma_f32_32x32x16_bf16 v[176:191], v[212:215], v[74:77], v[176:191]
	v_sub_f32_e32 v47, v47, v112
	v_exp_f32_e32 v46, v46
	v_cvt_pk_bf16_f32 v52, v54, v55
	v_sub_f32_e32 v48, v48, v112
	v_exp_f32_e32 v47, v47
	v_sub_f32_e32 v49, v49, v112
	v_cvt_pk_bf16_f32 v53, v56, v57
	v_exp_f32_e32 v48, v48
	v_exp_f32_e32 v49, v49
	v_cvt_pk_bf16_f32 v58, v58, v59
	v_cvt_pk_bf16_f32 v59, v60, v61
	v_cvt_pk_bf16_f32 v60, v62, v63
	v_cvt_pk_bf16_f32 v61, v64, v65
	v_pk_add_f32 v[116:117], v[116:117], v[34:35]
	s_waitcnt lgkmcnt(5)
	v_mfma_f32_32x32x16_bf16 v[160:175], v[216:219], v[78:81], v[160:175]
	v_pk_add_f32 v[118:119], v[118:119], v[36:37]
	v_pk_add_f32 v[116:117], v[116:117], v[38:39]
	v_pk_add_f32 v[118:119], v[118:119], v[40:41]
	v_pk_add_f32 v[116:117], v[116:117], v[42:43]
	v_pk_add_f32 v[118:119], v[118:119], v[44:45]
	v_pk_add_f32 v[116:117], v[116:117], v[46:47]
	v_pk_add_f32 v[118:119], v[118:119], v[48:49]
	v_pk_add_f32 v[116:117], v[116:117], v[118:119]
	v_cvt_pk_bf16_f32 v34, v34, v35
	v_cvt_pk_bf16_f32 v35, v36, v37
	v_cvt_pk_bf16_f32 v36, v38, v39
	v_cvt_pk_bf16_f32 v37, v40, v41
	s_waitcnt lgkmcnt(4)
	v_mfma_f32_32x32x16_bf16 v[176:191], v[220:223], v[78:81], v[176:191]
	v_cvt_pk_bf16_f32 v42, v42, v43
	v_cvt_pk_bf16_f32 v43, v44, v45
	ds_read2_b64 v[192:195], v247 offset0:128 offset1:130
	ds_read2_b64 v[196:199], v246 offset0:192 offset1:194
	ds_read2_b64 v[200:203], v247 offset0:132 offset1:134
	ds_read2_b64 v[204:207], v246 offset0:196 offset1:198
	ds_read2_b64 v[208:211], v247 offset0:136 offset1:138
	ds_read2_b64 v[212:215], v246 offset0:200 offset1:202
	ds_read2_b64 v[216:219], v247 offset0:140 offset1:142
	ds_read2_b64 v[220:223], v246 offset0:204 offset1:206
	v_cvt_pk_bf16_f32 v44, v46, v47
	v_cvt_pk_bf16_f32 v45, v48, v49
	v_add_f32_e32 v116, v116, v117
	v_pk_mul_f32 v[18:19], v[18:19], v[114:115] op_sel_hi:[1,0]
	v_pk_mul_f32 v[20:21], v[20:21], v[114:115] op_sel_hi:[1,0]
	v_fma_f32 v121, v111, v114, v116
	v_pk_mul_f32 v[22:23], v[22:23], v[114:115] op_sel_hi:[1,0]
	v_pk_mul_f32 v[24:25], v[24:25], v[114:115] op_sel_hi:[1,0]
	v_pk_mul_f32 v[26:27], v[26:27], v[114:115] op_sel_hi:[1,0]
	v_pk_mul_f32 v[28:29], v[28:29], v[114:115] op_sel_hi:[1,0]
	v_pk_mul_f32 v[30:31], v[30:31], v[114:115] op_sel_hi:[1,0]
	v_pk_mul_f32 v[32:33], v[32:33], v[114:115] op_sel_hi:[1,0]
	v_pk_mul_f32 v[2:3], v[2:3], v[114:115] op_sel_hi:[1,0]
	v_pk_mul_f32 v[4:5], v[4:5], v[114:115] op_sel_hi:[1,0]
	v_pk_mul_f32 v[6:7], v[6:7], v[114:115] op_sel_hi:[1,0]
	v_pk_mul_f32 v[8:9], v[8:9], v[114:115] op_sel_hi:[1,0]
	v_pk_mul_f32 v[10:11], v[10:11], v[114:115] op_sel_hi:[1,0]
	v_pk_mul_f32 v[12:13], v[12:13], v[114:115] op_sel_hi:[1,0]
	v_pk_mul_f32 v[14:15], v[14:15], v[114:115] op_sel_hi:[1,0]
	v_pk_mul_f32 v[16:17], v[16:17], v[114:115] op_sel_hi:[1,0]
	s_cmp_ge_i32 s53, s36
	s_cbranch_scc1 .Lap_nomask1
	s_add_i32 s54, s44, s53
	s_abs_i32 s54, s54
	s_cmp_lg_u32 s54, 2
	s_cbranch_scc1 .Lap_nomask1
	v_add_u32_e32 v120, 64, v99
	v_cmp_lt_u32_e32 vcc, s33, v120
	v_add_u32_e32 v245, 0x60, v99
	s_nop 0
	v_cndmask_b32_e32 v160, v234, v160, vcc
	v_cmp_lt_u32_e32 vcc, s33, v245
	v_add_u32_e32 v120, 0x41, v99
	s_nop 0
	v_cndmask_b32_e32 v176, v234, v176, vcc
	v_cmp_lt_u32_e32 vcc, s33, v120
	v_add_u32_e32 v245, 0x61, v99
	s_nop 0
	v_cndmask_b32_e32 v161, v234, v161, vcc
	v_cmp_lt_u32_e32 vcc, s33, v245
	v_add_u32_e32 v120, 0x42, v99
	s_nop 0
	v_cndmask_b32_e32 v177, v234, v177, vcc
	v_cmp_lt_u32_e32 vcc, s33, v120
	v_add_u32_e32 v245, 0x62, v99
	s_nop 0
	v_cndmask_b32_e32 v162, v234, v162, vcc
	v_cmp_lt_u32_e32 vcc, s33, v245
	v_add_u32_e32 v120, 0x43, v99
	s_nop 0
	v_cndmask_b32_e32 v178, v234, v178, vcc
	v_cmp_lt_u32_e32 vcc, s33, v120
	v_add_u32_e32 v245, 0x63, v99
	s_nop 0
	v_cndmask_b32_e32 v163, v234, v163, vcc
	v_cmp_lt_u32_e32 vcc, s33, v245
	v_add_u32_e32 v120, 0x48, v99
	s_nop 0
	v_cndmask_b32_e32 v179, v234, v179, vcc
	v_cmp_lt_u32_e32 vcc, s33, v120
	v_add_u32_e32 v245, 0x68, v99
	s_nop 0
	v_cndmask_b32_e32 v164, v234, v164, vcc
	v_cmp_lt_u32_e32 vcc, s33, v245
	v_add_u32_e32 v120, 0x49, v99
	s_nop 0
	v_cndmask_b32_e32 v180, v234, v180, vcc
	v_cmp_lt_u32_e32 vcc, s33, v120
	v_add_u32_e32 v245, 0x69, v99
	s_nop 0
	v_cndmask_b32_e32 v165, v234, v165, vcc
	v_cmp_lt_u32_e32 vcc, s33, v245
	v_add_u32_e32 v120, 0x4a, v99
	s_nop 0
	v_cndmask_b32_e32 v181, v234, v181, vcc
	v_cmp_lt_u32_e32 vcc, s33, v120
	v_add_u32_e32 v245, 0x6a, v99
	s_nop 0
	v_cndmask_b32_e32 v166, v234, v166, vcc
	v_cmp_lt_u32_e32 vcc, s33, v245
	v_add_u32_e32 v120, 0x4b, v99
	s_nop 0
	v_cndmask_b32_e32 v182, v234, v182, vcc
	v_cmp_lt_u32_e32 vcc, s33, v120
	v_add_u32_e32 v245, 0x6b, v99
	s_nop 0
	v_cndmask_b32_e32 v167, v234, v167, vcc
	v_cmp_lt_u32_e32 vcc, s33, v245
	v_add_u32_e32 v120, 0x50, v99
	s_nop 0
	v_cndmask_b32_e32 v183, v234, v183, vcc
	v_cmp_lt_u32_e32 vcc, s33, v120
	v_add_u32_e32 v245, 0x70, v99
	s_nop 0
	v_cndmask_b32_e32 v168, v234, v168, vcc
	v_cmp_lt_u32_e32 vcc, s33, v245
	v_add_u32_e32 v120, 0x51, v99
	s_nop 0
	v_cndmask_b32_e32 v184, v234, v184, vcc
	v_cmp_lt_u32_e32 vcc, s33, v120
	v_add_u32_e32 v245, 0x71, v99
	s_nop 0
	v_cndmask_b32_e32 v169, v234, v169, vcc
	v_cmp_lt_u32_e32 vcc, s33, v245
	v_add_u32_e32 v120, 0x52, v99
	s_nop 0
	v_cndmask_b32_e32 v185, v234, v185, vcc
	v_cmp_lt_u32_e32 vcc, s33, v120
	v_add_u32_e32 v245, 0x72, v99
	s_nop 0
	v_cndmask_b32_e32 v170, v234, v170, vcc
	v_cmp_lt_u32_e32 vcc, s33, v245
	v_add_u32_e32 v120, 0x53, v99
	s_nop 0
	v_cndmask_b32_e32 v186, v234, v186, vcc
	v_cmp_lt_u32_e32 vcc, s33, v120
	v_add_u32_e32 v245, 0x73, v99
	s_nop 0
	v_cndmask_b32_e32 v171, v234, v171, vcc
	v_cmp_lt_u32_e32 vcc, s33, v245
	v_add_u32_e32 v120, 0x58, v99
	s_nop 0
	v_cndmask_b32_e32 v187, v234, v187, vcc
	v_cmp_lt_u32_e32 vcc, s33, v120
	v_add_u32_e32 v245, 0x78, v99
	s_nop 0
	v_cndmask_b32_e32 v172, v234, v172, vcc
	v_cmp_lt_u32_e32 vcc, s33, v245
	v_add_u32_e32 v120, 0x59, v99
	s_nop 0
	v_cndmask_b32_e32 v188, v234, v188, vcc
	v_cmp_lt_u32_e32 vcc, s33, v120
	v_add_u32_e32 v245, 0x79, v99
	s_nop 0
	v_cndmask_b32_e32 v173, v234, v173, vcc
	v_cmp_lt_u32_e32 vcc, s33, v245
	v_add_u32_e32 v120, 0x5a, v99
	s_nop 0
	v_cndmask_b32_e32 v189, v234, v189, vcc
	v_cmp_lt_u32_e32 vcc, s33, v120
	v_add_u32_e32 v245, 0x7a, v99
	s_nop 0
	v_cndmask_b32_e32 v174, v234, v174, vcc
	v_cmp_lt_u32_e32 vcc, s33, v245
	v_add_u32_e32 v120, 0x5b, v99
	s_nop 0
	v_cndmask_b32_e32 v190, v234, v190, vcc
	v_cmp_lt_u32_e32 vcc, s33, v120
	v_add_u32_e32 v245, 0x7b, v99
	s_nop 0
	v_cndmask_b32_e32 v175, v234, v175, vcc
	v_cmp_lt_u32_e32 vcc, s33, v245
	s_nop 0
	s_nop 0
	v_cndmask_b32_e32 v191, v234, v191, vcc
.Lap_nomask1:
	v_max3_f32 v102, v160, v161, v162
	v_max3_f32 v103, v176, v177, v178
	v_max3_f32 v102, v102, v163, v164
	v_max3_f32 v103, v103, v179, v180
	v_max3_f32 v102, v102, v165, v166
	v_max3_f32 v103, v103, v181, v182
	s_waitcnt lgkmcnt(11)
	v_mfma_f32_32x32x16_bf16 v[18:33], v[122:125], v[50:53], v[18:33]
	v_max3_f32 v102, v102, v167, v168
	v_max3_f32 v103, v103, v183, v184
	v_max3_f32 v102, v102, v169, v170
	v_max3_f32 v103, v103, v185, v186
	v_max3_f32 v102, v102, v171, v172
	v_max3_f32 v103, v103, v187, v188
	v_max3_f32 v102, v102, v173, v174
	v_max3_f32 v103, v103, v189, v190
	v_max3_f32 v102, v102, v175, v191
	v_max_f32_e32 v102, v102, v103
	v_mov_b32_e32 v110, v102
	s_nop 1
	v_permlane32_swap_b32_e32 v110, v102
	s_nop 1
	s_waitcnt lgkmcnt(10)
	v_mfma_f32_32x32x16_bf16 v[2:17], v[126:129], v[50:53], v[2:17]
	v_max3_f32 v107, v112, v110, v102
	v_sub_f32_e32 v120, v112, v107
	v_sub_f32_e32 v160, v160, v107
	v_sub_f32_e32 v161, v161, v107
	v_exp_f32_e32 v114, v120
	v_exp_f32_e32 v160, v160
	v_sub_f32_e32 v162, v162, v107
	v_exp_f32_e32 v161, v161
	v_sub_f32_e32 v163, v163, v107
	v_exp_f32_e32 v162, v162
	v_sub_f32_e32 v164, v164, v107
	v_exp_f32_e32 v163, v163
	v_sub_f32_e32 v165, v165, v107
	v_exp_f32_e32 v164, v164
	s_waitcnt lgkmcnt(9)
	v_mfma_f32_32x32x16_bf16 v[18:33], v[130:133], v[58:61], v[18:33]
	v_sub_f32_e32 v166, v166, v107
	v_exp_f32_e32 v165, v165
	v_sub_f32_e32 v167, v167, v107
	v_exp_f32_e32 v166, v166
	v_sub_f32_e32 v168, v168, v107
	v_exp_f32_e32 v167, v167
	v_sub_f32_e32 v169, v169, v107
	v_exp_f32_e32 v168, v168
	v_sub_f32_e32 v170, v170, v107
	v_exp_f32_e32 v169, v169
	v_sub_f32_e32 v171, v171, v107
	v_exp_f32_e32 v170, v170
	v_sub_f32_e32 v172, v172, v107
	v_exp_f32_e32 v171, v171
	s_waitcnt lgkmcnt(8)
	v_mfma_f32_32x32x16_bf16 v[2:17], v[134:137], v[58:61], v[2:17]
	ds_read2_b64 v[122:125], v243 offset0:136 offset1:138
	ds_read2_b64 v[126:129], v244 offset0:200 offset1:202
	ds_read2_b64 v[130:133], v243 offset0:140 offset1:142
	ds_read2_b64 v[134:137], v244 offset0:204 offset1:206
	v_sub_f32_e32 v173, v173, v107
	v_exp_f32_e32 v172, v172
	v_sub_f32_e32 v174, v174, v107
	v_exp_f32_e32 v173, v173
	v_sub_f32_e32 v175, v175, v107
	v_exp_f32_e32 v174, v174
	v_exp_f32_e32 v175, v175
	v_sub_f32_e32 v176, v176, v107
	v_sub_f32_e32 v177, v177, v107
	v_exp_f32_e32 v176, v176
	v_pk_add_f32 v[116:117], v[160:161], v[162:163]
	v_sub_f32_e32 v178, v178, v107
	v_exp_f32_e32 v177, v177
	v_sub_f32_e32 v179, v179, v107
	s_waitcnt lgkmcnt(3)
	v_mfma_f32_32x32x16_bf16 v[18:33], v[122:125], v[34:37], v[18:33]
	v_pk_add_f32 v[118:119], v[164:165], v[166:167]
	v_exp_f32_e32 v178, v178
	v_sub_f32_e32 v180, v180, v107
	v_exp_f32_e32 v179, v179
	v_pk_add_f32 v[116:117], v[116:117], v[168:169]
	v_sub_f32_e32 v181, v181, v107
	v_exp_f32_e32 v180, v180
	v_sub_f32_e32 v182, v182, v107
	v_pk_add_f32 v[118:119], v[118:119], v[170:171]
	v_exp_f32_e32 v181, v181
	v_sub_f32_e32 v183, v183, v107
	v_exp_f32_e32 v182, v182
	v_pk_add_f32 v[116:117], v[116:117], v[172:173]
	v_sub_f32_e32 v184, v184, v107
	s_waitcnt lgkmcnt(2)
	v_mfma_f32_32x32x16_bf16 v[2:17], v[126:129], v[34:37], v[2:17]
	v_exp_f32_e32 v183, v183
	v_sub_f32_e32 v185, v185, v107
	v_pk_add_f32 v[118:119], v[118:119], v[174:175]
	v_exp_f32_e32 v184, v184
	v_sub_f32_e32 v186, v186, v107
	v_exp_f32_e32 v185, v185
	v_cvt_pk_bf16_f32 v160, v160, v161
	v_sub_f32_e32 v187, v187, v107
	v_exp_f32_e32 v186, v186
	v_sub_f32_e32 v188, v188, v107
	v_cvt_pk_bf16_f32 v161, v162, v163
	v_exp_f32_e32 v187, v187
	v_sub_f32_e32 v189, v189, v107
	v_exp_f32_e32 v188, v188
	s_waitcnt lgkmcnt(1)
	v_mfma_f32_32x32x16_bf16 v[18:33], v[130:133], v[42:45], v[18:33]
	v_cvt_pk_bf16_f32 v162, v164, v165
	v_sub_f32_e32 v190, v190, v107
	v_exp_f32_e32 v189, v189
	v_sub_f32_e32 v191, v191, v107
	v_cvt_pk_bf16_f32 v163, v166, v167
	v_exp_f32_e32 v190, v190
	v_exp_f32_e32 v191, v191
	v_cvt_pk_bf16_f32 v168, v168, v169
	v_cvt_pk_bf16_f32 v169, v170, v171
	v_cvt_pk_bf16_f32 v170, v172, v173
	v_cvt_pk_bf16_f32 v171, v174, v175
	v_pk_add_f32 v[116:117], v[116:117], v[176:177]
	v_pk_add_f32 v[118:119], v[118:119], v[178:179]
	v_pk_add_f32 v[116:117], v[116:117], v[180:181]
	s_waitcnt lgkmcnt(0)
	v_mfma_f32_32x32x16_bf16 v[2:17], v[134:137], v[42:45], v[2:17]
	v_pk_add_f32 v[118:119], v[118:119], v[182:183]
	v_pk_add_f32 v[116:117], v[116:117], v[184:185]
	v_pk_add_f32 v[118:119], v[118:119], v[186:187]
	v_pk_add_f32 v[116:117], v[116:117], v[188:189]
	v_pk_add_f32 v[118:119], v[118:119], v[190:191]
	v_pk_add_f32 v[116:117], v[116:117], v[118:119]
	v_cvt_pk_bf16_f32 v176, v176, v177
	v_cvt_pk_bf16_f32 v177, v178, v179
	v_cvt_pk_bf16_f32 v178, v180, v181
	v_cvt_pk_bf16_f32 v179, v182, v183
	v_cvt_pk_bf16_f32 v184, v184, v185
	v_cvt_pk_bf16_f32 v185, v186, v187
	v_cvt_pk_bf16_f32 v186, v188, v189
	v_cvt_pk_bf16_f32 v187, v190, v191
	v_add_f32_e32 v116, v116, v117
	v_pk_mul_f32 v[18:19], v[18:19], v[114:115] op_sel_hi:[1,0]
	v_pk_mul_f32 v[20:21], v[20:21], v[114:115] op_sel_hi:[1,0]
	v_fma_f32 v106, v121, v114, v116
	v_pk_mul_f32 v[22:23], v[22:23], v[114:115] op_sel_hi:[1,0]
	v_pk_mul_f32 v[24:25], v[24:25], v[114:115] op_sel_hi:[1,0]
	v_pk_mul_f32 v[26:27], v[26:27], v[114:115] op_sel_hi:[1,0]
	v_pk_mul_f32 v[28:29], v[28:29], v[114:115] op_sel_hi:[1,0]
	v_pk_mul_f32 v[30:31], v[30:31], v[114:115] op_sel_hi:[1,0]
	v_pk_mul_f32 v[32:33], v[32:33], v[114:115] op_sel_hi:[1,0]
	v_pk_mul_f32 v[2:3], v[2:3], v[114:115] op_sel_hi:[1,0]
	v_pk_mul_f32 v[4:5], v[4:5], v[114:115] op_sel_hi:[1,0]
	v_pk_mul_f32 v[6:7], v[6:7], v[114:115] op_sel_hi:[1,0]
	v_pk_mul_f32 v[8:9], v[8:9], v[114:115] op_sel_hi:[1,0]
	v_pk_mul_f32 v[10:11], v[10:11], v[114:115] op_sel_hi:[1,0]
	v_pk_mul_f32 v[12:13], v[12:13], v[114:115] op_sel_hi:[1,0]
	v_pk_mul_f32 v[14:15], v[14:15], v[114:115] op_sel_hi:[1,0]
	v_pk_mul_f32 v[16:17], v[16:17], v[114:115] op_sel_hi:[1,0]
	s_nop 1
	v_mfma_f32_32x32x16_bf16 v[18:33], v[192:195], v[160:163], v[18:33]
	v_mfma_f32_32x32x16_bf16 v[2:17], v[196:199], v[160:163], v[2:17]
	v_mfma_f32_32x32x16_bf16 v[18:33], v[200:203], v[168:171], v[18:33]
	v_mfma_f32_32x32x16_bf16 v[2:17], v[204:207], v[168:171], v[2:17]
	v_mfma_f32_32x32x16_bf16 v[18:33], v[208:211], v[176:179], v[18:33]
	v_mfma_f32_32x32x16_bf16 v[2:17], v[212:215], v[176:179], v[2:17]
	v_mfma_f32_32x32x16_bf16 v[18:33], v[216:219], v[184:187], v[18:33]
	v_mfma_f32_32x32x16_bf16 v[2:17], v[220:223], v[184:187], v[2:17]
	s_branch .LBB0_573
